# k25 + one static s_setprio 1 for waves 4-7 during the attention phase (reset at phase exit)
# speedup vs baseline: 1.0065x; 1.0065x over previous
; __global__ void __launch_bounds__(NWAVES * 64, 2) mega_fwd(Args args) {
;     ...
;             const int vcu = (c.G % 8 == 0) ? (c.bid % 8) * (c.G / 8) + c.bid / 8 : c.bid;
;             for (int rep = 0; rep <= PROBE_ATTN; ++rep)
;             for (int i = vcu; i < 1024; i += c.G) {
;                 const int j = i >> 8, ii = i & 255, bh = ii >> 2, s4 = ii & 3;
;                 const int qb = (j == 0) ? 15 - s4 : (j == 1) ? 8 + s4 : (j == 2) ? 7 - s4 : s4;
;                 attn_unit(c, bh, qb, Qb, Kbuf, Vbuf, omix);
;             }
.LBB0_275:
	v_readlane_b32 s4, v254, 61
	s_nop 3
	s_cmp_lt_u32 s4, 0x100
	s_cbranch_scc1 .Lat_prio_done
	s_setprio 1

; __global__ void __launch_bounds__(NWAVES * 64, 2) mega_fwd(Args args) {
;     ...
;             for (int rep = 0; rep <= PROBE_ATTN; ++rep)
;             for (int i = vcu; i < 1024; i += c.G) {
;                 const int j = i >> 8, ii = i & 255, bh = ii >> 2, s4 = ii & 3;
;                 const int qb = (j == 0) ? 15 - s4 : (j == 1) ? 8 + s4 : (j == 2) ? 7 - s4 : s4;
;                 attn_unit(c, bh, qb, Qb, Kbuf, Vbuf, omix);
;             }
.LBB0_314:
	s_setprio 0
	s_mov_b64 s[6:7], 0
